# grid barrier: non-leader workgroups issue an un-waited L2 write-back on arrival so the XCD leader's write-back finds mostly clean lines
# speedup vs baseline: 1.0018x; 1.0018x over previous
.LBB0_217:
	s_lshl_b32 s1, s1, 8
	s_add_u32 s1, s38, s1
	s_addc_u32 s4, s39, 0
	v_mov_b32_e32 v1, s1
	v_add_co_u32_e32 v4, vcc, 0x2000, v1
	v_mov_b32_e32 v1, s4
	s_nop 0
	v_addc_co_u32_e32 v5, vcc, 0, v1, vcc
	v_mov_b32_e32 v1, 1
	flat_atomic_add v1, v[4:5], v1 offset:1024 sc0
	v_cvt_f32_u32_e32 v3, v2
	v_sub_u32_e32 v4, 0, v2
	s_add_u32 s3, s1, 0x1000
	s_addc_u32 s1, s4, 0
	v_rcp_iflag_f32_e32 v3, v3
	s_nop 0
	v_mul_f32_e32 v3, 0x4f7ffffe, v3
	v_cvt_u32_f32_e32 v3, v3
	v_mul_lo_u32 v4, v4, v3
	v_mul_hi_u32 v4, v3, v4
	v_add_u32_e32 v3, v3, v4
	s_waitcnt vmcnt(0) lgkmcnt(0)
	v_mul_hi_u32 v3, v1, v3
	v_mul_lo_u32 v5, v3, v2
	v_add_u32_e32 v4, 1, v1
	v_sub_u32_e32 v1, v1, v5
	v_add_u32_e32 v6, 1, v3
	v_cmp_ge_u32_e32 vcc, v1, v2
	v_sub_u32_e32 v5, v1, v2
	s_nop 0
	v_cndmask_b32_e32 v3, v3, v6, vcc
	v_cndmask_b32_e32 v1, v1, v5, vcc
	v_add_u32_e32 v5, 1, v3
	v_cmp_ge_u32_e32 vcc, v1, v2
	s_nop 1
	v_cndmask_b32_e32 v1, v3, v5, vcc
	v_mad_u64_u32 v[2:3], s[4:5], v2, v1, v[2:3]
	v_cmp_ne_u32_e32 vcc, v4, v2
	s_and_saveexec_b64 s[4:5], vcc
	s_xor_b64 s[4:5], exec, s[4:5]
	s_cbranch_execz .LBB0_230
	buffer_wbl2 sc1
	v_mov_b32_e32 v0, s3
	v_add_co_u32_e32 v2, vcc, 0x2000, v0
	v_mov_b32_e32 v0, s1
	s_nop 0
	v_addc_co_u32_e32 v3, vcc, 0, v0, vcc
	flat_load_dword v0, v[2:3] offset:1024 sc1
	s_add_u32 s10, s3, 0x2400
	s_addc_u32 s11, s1, 0
	s_waitcnt vmcnt(0) lgkmcnt(0)
	v_cmp_eq_u32_e32 vcc, v0, v1
	s_and_saveexec_b64 s[6:7], vcc
	s_cbranch_execz .LBB0_229
	s_add_u32 s8, s38, 0x1200
	s_addc_u32 s9, s39, 0
	s_mov_b32 s16, 1
	s_mov_b64 s[12:13], 0
	s_branch .LBB0_221

.LBB0_486:
	s_lshl_b32 s4, s54, 8
	s_add_u32 s4, s86, s4
	s_addc_u32 s5, s87, 0
	v_mov_b32_e32 v1, s4
	v_add_co_u32_e32 v4, vcc, 0x2000, v1
	v_mov_b32_e32 v1, s5
	s_nop 0
	v_addc_co_u32_e32 v5, vcc, 0, v1, vcc
	flat_atomic_add v1, v[4:5], v237 offset:1024 sc0
	v_cvt_f32_u32_e32 v3, v2
	v_sub_u32_e32 v4, 0, v2
	s_add_u32 s29, s4, 0x1000
	s_addc_u32 s28, s5, 0
	v_rcp_iflag_f32_e32 v3, v3
	s_nop 0
	v_mul_f32_e32 v3, 0x4f7ffffe, v3
	v_cvt_u32_f32_e32 v3, v3
	v_mul_lo_u32 v4, v4, v3
	v_mul_hi_u32 v4, v3, v4
	v_add_u32_e32 v3, v3, v4
	s_waitcnt vmcnt(0) lgkmcnt(0)
	v_mul_hi_u32 v3, v1, v3
	v_mul_lo_u32 v5, v3, v2
	v_add_u32_e32 v4, 1, v1
	v_sub_u32_e32 v1, v1, v5
	v_add_u32_e32 v6, 1, v3
	v_cmp_ge_u32_e32 vcc, v1, v2
	v_sub_u32_e32 v5, v1, v2
	s_nop 0
	v_cndmask_b32_e32 v3, v3, v6, vcc
	v_cndmask_b32_e32 v1, v1, v5, vcc
	v_add_u32_e32 v5, 1, v3
	v_cmp_ge_u32_e32 vcc, v1, v2
	s_nop 1
	v_cndmask_b32_e32 v1, v3, v5, vcc
	v_mad_u64_u32 v[2:3], s[4:5], v2, v1, v[2:3]
	v_cmp_ne_u32_e32 vcc, v4, v2
	s_and_saveexec_b64 s[4:5], vcc
	s_xor_b64 s[4:5], exec, s[4:5]
	s_cbranch_execz .LBB0_499
	buffer_wbl2 sc1
	v_mov_b32_e32 v0, s29
	v_add_co_u32_e32 v2, vcc, 0x2000, v0
	v_mov_b32_e32 v0, s28
	s_nop 0
	v_addc_co_u32_e32 v3, vcc, 0, v0, vcc
	flat_load_dword v0, v[2:3] offset:1024 sc1
	s_add_u32 s8, s29, 0x2400
	s_addc_u32 s9, s28, 0
	s_waitcnt vmcnt(0) lgkmcnt(0)
	v_cmp_eq_u32_e32 vcc, v0, v1
	s_and_saveexec_b64 s[6:7], vcc
	s_cbranch_execz .LBB0_498
	s_add_u32 s10, s86, 0x1200
	s_addc_u32 s11, s87, 0
	s_mov_b32 s30, 1
	s_mov_b64 s[12:13], 0
	s_branch .LBB0_490

.LBB0_897:
	s_lshl_b32 s6, s68, 8
	s_add_u32 s6, s88, s6
	s_addc_u32 s7, s89, 0
	v_mov_b32_e32 v1, s6
	v_add_co_u32_e32 v4, vcc, 0x2000, v1
	v_mov_b32_e32 v1, s7
	s_nop 0
	v_addc_co_u32_e32 v5, vcc, 0, v1, vcc
	flat_atomic_add v3, v[4:5], v237 offset:1024 sc0
	v_cvt_f32_u32_e32 v1, v2
	v_sub_u32_e32 v4, 0, v2
	s_add_u32 s31, s6, 0x1000
	s_addc_u32 s30, s7, 0
	v_rcp_iflag_f32_e32 v1, v1
	s_nop 0
	v_mul_f32_e32 v1, 0x4f7ffffe, v1
	v_cvt_u32_f32_e32 v1, v1
	v_mul_lo_u32 v4, v4, v1
	v_mul_hi_u32 v4, v1, v4
	v_add_u32_e32 v1, v1, v4
	s_waitcnt vmcnt(0) lgkmcnt(0)
	v_mul_hi_u32 v1, v3, v1
	v_mul_lo_u32 v4, v1, v2
	v_sub_u32_e32 v4, v3, v4
	v_cmp_ge_u32_e32 vcc, v4, v2
	v_add_u32_e32 v5, 1, v1
	s_nop 0
	v_cndmask_b32_e32 v1, v1, v5, vcc
	v_sub_u32_e32 v5, v4, v2
	v_cndmask_b32_e32 v4, v4, v5, vcc
	v_cmp_ge_u32_e32 vcc, v4, v2
	v_add_u32_e32 v4, 1, v1
	s_nop 0
	v_cndmask_b32_e32 v1, v1, v4, vcc
	v_add_u32_e32 v4, 1, v3
	v_mad_u64_u32 v[2:3], s[6:7], v2, v1, v[2:3]
	v_cmp_ne_u32_e32 vcc, v4, v2
	s_and_saveexec_b64 s[6:7], vcc
	s_xor_b64 s[6:7], exec, s[6:7]
	s_cbranch_execz .LBB0_910
	buffer_wbl2 sc1
	v_mov_b32_e32 v0, s31
	v_add_co_u32_e32 v2, vcc, 0x2000, v0
	v_mov_b32_e32 v0, s30
	s_nop 0
	v_addc_co_u32_e32 v3, vcc, 0, v0, vcc
	flat_load_dword v0, v[2:3] offset:1024 sc1
	s_add_u32 s10, s31, 0x2400
	s_addc_u32 s11, s30, 0
	s_waitcnt vmcnt(0) lgkmcnt(0)
	v_cmp_eq_u32_e32 vcc, v0, v1
	s_and_saveexec_b64 s[8:9], vcc
	s_cbranch_execz .LBB0_909
	s_add_u32 s12, s88, 0x1200
	s_addc_u32 s13, s89, 0
	s_mov_b32 s34, 1
	s_mov_b64 s[14:15], 0
	s_branch .LBB0_901

.LBB0_1042:
	s_lshl_b32 s1, s1, 8
	s_add_u32 s1, s86, s1
	s_addc_u32 s4, s87, 0
	v_mov_b32_e32 v1, s1
	v_add_co_u32_e32 v4, vcc, 0x2000, v1
	v_mov_b32_e32 v1, s4
	s_nop 0
	v_addc_co_u32_e32 v5, vcc, 0, v1, vcc
	flat_atomic_add v1, v[4:5], v237 offset:1024 sc0
	v_cvt_f32_u32_e32 v3, v2
	v_sub_u32_e32 v4, 0, v2
	s_add_u32 s28, s1, 0x1000
	s_addc_u32 s1, s4, 0
	v_rcp_iflag_f32_e32 v3, v3
	s_nop 0
	v_mul_f32_e32 v3, 0x4f7ffffe, v3
	v_cvt_u32_f32_e32 v3, v3
	v_mul_lo_u32 v4, v4, v3
	v_mul_hi_u32 v4, v3, v4
	v_add_u32_e32 v3, v3, v4
	s_waitcnt vmcnt(0) lgkmcnt(0)
	v_mul_hi_u32 v3, v1, v3
	v_mul_lo_u32 v5, v3, v2
	v_add_u32_e32 v4, 1, v1
	v_sub_u32_e32 v1, v1, v5
	v_add_u32_e32 v6, 1, v3
	v_cmp_ge_u32_e32 vcc, v1, v2
	v_sub_u32_e32 v5, v1, v2
	s_nop 0
	v_cndmask_b32_e32 v3, v3, v6, vcc
	v_cndmask_b32_e32 v1, v1, v5, vcc
	v_add_u32_e32 v5, 1, v3
	v_cmp_ge_u32_e32 vcc, v1, v2
	s_nop 1
	v_cndmask_b32_e32 v1, v3, v5, vcc
	v_mad_u64_u32 v[2:3], s[4:5], v2, v1, v[2:3]
	v_cmp_ne_u32_e32 vcc, v4, v2
	s_and_saveexec_b64 s[4:5], vcc
	s_xor_b64 s[4:5], exec, s[4:5]
	s_cbranch_execz .LBB0_1055
	buffer_wbl2 sc1
	v_mov_b32_e32 v0, s28
	v_add_co_u32_e32 v2, vcc, 0x2000, v0
	v_mov_b32_e32 v0, s1
	s_nop 0
	v_addc_co_u32_e32 v3, vcc, 0, v0, vcc
	flat_load_dword v0, v[2:3] offset:1024 sc1
	s_add_u32 s8, s28, 0x2400
	s_addc_u32 s9, s1, 0
	s_waitcnt vmcnt(0) lgkmcnt(0)
	v_cmp_eq_u32_e32 vcc, v0, v1
	s_and_saveexec_b64 s[6:7], vcc
	s_cbranch_execz .LBB0_1054
	s_add_u32 s10, s86, 0x1200
	s_addc_u32 s11, s87, 0
	s_mov_b32 s29, 1
	s_mov_b64 s[12:13], 0
	s_branch .LBB0_1046
